# v11 + grid-barrier followers poll the top-level generation word directly instead of the per-XCD generation (one fewer hop per seam)
# baseline (speedup 1.0000x reference)
.LBB0_427:
	s_or_b64 exec, exec, s[12:13]
	v_cvt_f32_u32_e32 v5, v3
	s_waitcnt vmcnt(0)
	v_readfirstlane_b32 s3, v4
	v_sub_u32_e32 v4, 0, v3
	v_rcp_iflag_f32_e32 v5, v5
	v_add_u32_e32 v6, s3, v2
	v_mul_f32_e32 v5, 0x4f7ffffe, v5
	v_cvt_u32_f32_e32 v5, v5
	v_mul_lo_u32 v2, v4, v5
	v_mul_hi_u32 v2, v5, v2
	v_add_u32_e32 v2, v5, v2
	v_mul_hi_u32 v2, v6, v2
	v_mul_lo_u32 v4, v2, v3
	v_sub_u32_e32 v4, v6, v4
	v_add_u32_e32 v5, 1, v2
	v_cmp_ge_u32_e32 vcc, v4, v3
	s_nop 1
	v_cndmask_b32_e32 v2, v2, v5, vcc
	v_sub_u32_e32 v5, v4, v3
	v_cndmask_b32_e32 v4, v4, v5, vcc
	v_add_u32_e32 v5, 1, v2
	v_cmp_ge_u32_e32 vcc, v4, v3
	v_add_u32_e32 v4, 1, v6
	s_nop 0
	v_cndmask_b32_e32 v2, v2, v5, vcc
	v_mul_lo_u32 v5, v3, v2
	v_add_u32_e32 v3, v5, v3
	v_cmp_ne_u32_e32 vcc, v4, v3
	s_and_saveexec_b64 s[10:11], vcc
	s_xor_b64 s[10:11], exec, s[10:11]
	s_cbranch_execz .LBB0_441
	s_waitcnt lgkmcnt(0)
	s_add_u32 s16, s30, 0x7500
	s_addc_u32 s17, s31, 0
	v_mov_b32_e32 v1, 0
	global_load_dword v1, v1, s[16:17] sc1
	s_waitcnt vmcnt(0)
	v_cmp_eq_u32_e32 vcc, v1, v2
	s_and_saveexec_b64 s[12:13], vcc
	s_cbranch_execz .LBB0_440
	s_add_u32 s14, s30, 0x4200
	s_addc_u32 s15, s31, 0
	s_mov_b32 s3, 1
	s_mov_b64 s[18:19], 0
	v_mov_b32_e32 v1, 0
	s_branch .LBB0_431

.LBB0_574:
	s_or_b64 exec, exec, s[12:13]
	v_cvt_f32_u32_e32 v5, v3
	s_waitcnt vmcnt(0)
	v_readfirstlane_b32 s10, v4
	v_sub_u32_e32 v4, 0, v3
	v_rcp_iflag_f32_e32 v5, v5
	v_add_u32_e32 v6, s10, v2
	v_mul_f32_e32 v5, 0x4f7ffffe, v5
	v_cvt_u32_f32_e32 v5, v5
	v_mul_lo_u32 v2, v4, v5
	v_mul_hi_u32 v2, v5, v2
	v_add_u32_e32 v2, v5, v2
	v_mul_hi_u32 v2, v6, v2
	v_mul_lo_u32 v4, v2, v3
	v_sub_u32_e32 v4, v6, v4
	v_add_u32_e32 v5, 1, v2
	v_cmp_ge_u32_e32 vcc, v4, v3
	s_nop 1
	v_cndmask_b32_e32 v2, v2, v5, vcc
	v_sub_u32_e32 v5, v4, v3
	v_cndmask_b32_e32 v4, v4, v5, vcc
	v_add_u32_e32 v5, 1, v2
	v_cmp_ge_u32_e32 vcc, v4, v3
	v_add_u32_e32 v4, 1, v6
	s_nop 0
	v_cndmask_b32_e32 v2, v2, v5, vcc
	v_mul_lo_u32 v5, v3, v2
	v_add_u32_e32 v3, v5, v3
	v_cmp_ne_u32_e32 vcc, v4, v3
	s_and_saveexec_b64 s[10:11], vcc
	s_xor_b64 s[10:11], exec, s[10:11]
	s_cbranch_execz .LBB0_588
	s_waitcnt lgkmcnt(0)
	s_add_u32 s16, s30, 0x7500
	s_addc_u32 s17, s31, 0
	v_mov_b32_e32 v1, 0
	global_load_dword v1, v1, s[16:17] sc1
	s_waitcnt vmcnt(0)
	v_cmp_eq_u32_e32 vcc, v1, v2
	s_and_saveexec_b64 s[12:13], vcc
	s_cbranch_execz .LBB0_587
	s_add_u32 s14, s30, 0x4200
	s_addc_u32 s15, s31, 0
	s_mov_b32 s27, 1
	s_mov_b64 s[18:19], 0
	v_mov_b32_e32 v1, 0
	s_branch .LBB0_578

.LBB0_1118:
	s_or_b64 exec, exec, s[12:13]
	v_cvt_f32_u32_e32 v5, v3
	s_waitcnt vmcnt(0)
	v_readfirstlane_b32 s10, v4
	v_sub_u32_e32 v4, 0, v3
	v_rcp_iflag_f32_e32 v5, v5
	v_add_u32_e32 v6, s10, v2
	v_mul_f32_e32 v5, 0x4f7ffffe, v5
	v_cvt_u32_f32_e32 v5, v5
	v_mul_lo_u32 v2, v4, v5
	v_mul_hi_u32 v2, v5, v2
	v_add_u32_e32 v2, v5, v2
	v_mul_hi_u32 v2, v6, v2
	v_mul_lo_u32 v4, v2, v3
	v_sub_u32_e32 v4, v6, v4
	v_add_u32_e32 v5, 1, v2
	v_cmp_ge_u32_e32 vcc, v4, v3
	s_nop 1
	v_cndmask_b32_e32 v2, v2, v5, vcc
	v_sub_u32_e32 v5, v4, v3
	v_cndmask_b32_e32 v4, v4, v5, vcc
	v_add_u32_e32 v5, 1, v2
	v_cmp_ge_u32_e32 vcc, v4, v3
	v_add_u32_e32 v4, 1, v6
	s_nop 0
	v_cndmask_b32_e32 v2, v2, v5, vcc
	v_mul_lo_u32 v5, v3, v2
	v_add_u32_e32 v3, v5, v3
	v_cmp_ne_u32_e32 vcc, v4, v3
	s_and_saveexec_b64 s[10:11], vcc
	s_xor_b64 s[10:11], exec, s[10:11]
	s_cbranch_execz .LBB0_1132
	s_waitcnt lgkmcnt(0)
	s_add_u32 s18, s30, 0x7500
	s_addc_u32 s19, s31, 0
	v_mov_b32_e32 v1, 0
	global_load_dword v1, v1, s[18:19] sc1
	s_waitcnt vmcnt(0)
	v_cmp_eq_u32_e32 vcc, v1, v2
	s_and_saveexec_b64 s[12:13], vcc
	s_cbranch_execz .LBB0_1131
	s_add_u32 s14, s30, 0x4200
	s_addc_u32 s15, s31, 0
	s_mov_b32 s27, 1
	s_mov_b64 s[20:21], 0
	v_mov_b32_e32 v1, 0
	s_branch .LBB0_1122

.LBB0_1181:
	s_or_b64 exec, exec, s[12:13]
	v_cvt_f32_u32_e32 v5, v3
	s_waitcnt vmcnt(0)
	v_readfirstlane_b32 s10, v4
	v_sub_u32_e32 v4, 0, v3
	v_rcp_iflag_f32_e32 v5, v5
	v_add_u32_e32 v6, s10, v2
	v_mul_f32_e32 v5, 0x4f7ffffe, v5
	v_cvt_u32_f32_e32 v5, v5
	v_mul_lo_u32 v2, v4, v5
	v_mul_hi_u32 v2, v5, v2
	v_add_u32_e32 v2, v5, v2
	v_mul_hi_u32 v2, v6, v2
	v_mul_lo_u32 v4, v2, v3
	v_sub_u32_e32 v4, v6, v4
	v_add_u32_e32 v5, 1, v2
	v_cmp_ge_u32_e32 vcc, v4, v3
	s_nop 1
	v_cndmask_b32_e32 v2, v2, v5, vcc
	v_sub_u32_e32 v5, v4, v3
	v_cndmask_b32_e32 v4, v4, v5, vcc
	v_add_u32_e32 v5, 1, v2
	v_cmp_ge_u32_e32 vcc, v4, v3
	v_add_u32_e32 v4, 1, v6
	s_nop 0
	v_cndmask_b32_e32 v2, v2, v5, vcc
	v_mul_lo_u32 v5, v3, v2
	v_add_u32_e32 v3, v5, v3
	v_cmp_ne_u32_e32 vcc, v4, v3
	s_and_saveexec_b64 s[10:11], vcc
	s_xor_b64 s[10:11], exec, s[10:11]
	s_cbranch_execz .LBB0_1195
	s_waitcnt lgkmcnt(0)
	s_add_u32 s16, s30, 0x7500
	s_addc_u32 s17, s31, 0
	v_mov_b32_e32 v1, 0
	global_load_dword v1, v1, s[16:17] sc1
	s_waitcnt vmcnt(0)
	v_cmp_eq_u32_e32 vcc, v1, v2
	s_and_saveexec_b64 s[12:13], vcc
	s_cbranch_execz .LBB0_1194
	s_add_u32 s14, s30, 0x4200
	s_addc_u32 s15, s31, 0
	s_mov_b32 s38, 1
	s_mov_b64 s[18:19], 0
	v_mov_b32_e32 v1, 0
	s_branch .LBB0_1185

.LBB0_1520:
	s_or_b64 exec, exec, s[12:13]
	v_cvt_f32_u32_e32 v5, v3
	s_waitcnt vmcnt(0)
	v_readfirstlane_b32 s10, v4
	v_sub_u32_e32 v4, 0, v3
	v_rcp_iflag_f32_e32 v5, v5
	v_add_u32_e32 v6, s10, v2
	v_mul_f32_e32 v5, 0x4f7ffffe, v5
	v_cvt_u32_f32_e32 v5, v5
	v_mul_lo_u32 v2, v4, v5
	v_mul_hi_u32 v2, v5, v2
	v_add_u32_e32 v2, v5, v2
	v_mul_hi_u32 v2, v6, v2
	v_mul_lo_u32 v4, v2, v3
	v_sub_u32_e32 v4, v6, v4
	v_add_u32_e32 v5, 1, v2
	v_cmp_ge_u32_e32 vcc, v4, v3
	s_nop 1
	v_cndmask_b32_e32 v2, v2, v5, vcc
	v_sub_u32_e32 v5, v4, v3
	v_cndmask_b32_e32 v4, v4, v5, vcc
	v_add_u32_e32 v5, 1, v2
	v_cmp_ge_u32_e32 vcc, v4, v3
	v_add_u32_e32 v4, 1, v6
	s_nop 0
	v_cndmask_b32_e32 v2, v2, v5, vcc
	v_mul_lo_u32 v5, v3, v2
	v_add_u32_e32 v3, v5, v3
	v_cmp_ne_u32_e32 vcc, v4, v3
	s_and_saveexec_b64 s[10:11], vcc
	s_xor_b64 s[10:11], exec, s[10:11]
	s_cbranch_execz .LBB0_1534
	s_waitcnt lgkmcnt(0)
	s_add_u32 s18, s30, 0x7500
	s_addc_u32 s19, s31, 0
	v_mov_b32_e32 v1, 0
	global_load_dword v1, v1, s[18:19] sc1
	s_waitcnt vmcnt(0)
	v_cmp_eq_u32_e32 vcc, v1, v2
	s_and_saveexec_b64 s[12:13], vcc
	s_cbranch_execz .LBB0_1533
	s_add_u32 s16, s30, 0x4200
	s_addc_u32 s17, s31, 0
	s_mov_b32 s27, 1
	s_mov_b64 s[20:21], 0
	v_mov_b32_e32 v1, 0
	s_branch .LBB0_1524

.LBB0_1585:
	s_or_b64 exec, exec, s[14:15]
	v_cvt_f32_u32_e32 v6, v4
	s_waitcnt vmcnt(0)
	v_readfirstlane_b32 s10, v5
	v_sub_u32_e32 v5, 0, v4
	v_rcp_iflag_f32_e32 v6, v6
	v_add_u32_e32 v7, s10, v3
	v_mul_f32_e32 v6, 0x4f7ffffe, v6
	v_cvt_u32_f32_e32 v6, v6
	v_mul_lo_u32 v3, v5, v6
	v_mul_hi_u32 v3, v6, v3
	v_add_u32_e32 v3, v6, v3
	v_mul_hi_u32 v3, v7, v3
	v_mul_lo_u32 v5, v3, v4
	v_sub_u32_e32 v5, v7, v5
	v_add_u32_e32 v6, 1, v3
	v_cmp_ge_u32_e32 vcc, v5, v4
	s_nop 1
	v_cndmask_b32_e32 v3, v3, v6, vcc
	v_sub_u32_e32 v6, v5, v4
	v_cndmask_b32_e32 v5, v5, v6, vcc
	v_add_u32_e32 v6, 1, v3
	v_cmp_ge_u32_e32 vcc, v5, v4
	v_add_u32_e32 v5, 1, v7
	s_nop 0
	v_cndmask_b32_e32 v3, v3, v6, vcc
	v_mul_lo_u32 v6, v4, v3
	v_add_u32_e32 v4, v6, v4
	v_cmp_ne_u32_e32 vcc, v5, v4
	s_and_saveexec_b64 s[10:11], vcc
	s_xor_b64 s[10:11], exec, s[10:11]
	s_cbranch_execz .LBB0_1599
	s_waitcnt lgkmcnt(0)
	s_add_u32 s18, s30, 0x7500
	s_addc_u32 s19, s31, 0
	v_mov_b32_e32 v2, 0
	global_load_dword v2, v2, s[18:19] sc1
	s_waitcnt vmcnt(0)
	v_cmp_eq_u32_e32 vcc, v2, v3
	s_and_saveexec_b64 s[14:15], vcc
	s_cbranch_execz .LBB0_1598
	s_add_u32 s16, s30, 0x4200
	s_addc_u32 s17, s31, 0
	s_mov_b32 s27, 1
	s_mov_b64 s[20:21], 0
	v_mov_b32_e32 v2, 0
	s_branch .LBB0_1589

.LBB0_1733:
	s_or_b64 exec, exec, s[16:17]
	v_cvt_f32_u32_e32 v6, v4
	s_waitcnt vmcnt(0)
	v_readfirstlane_b32 s14, v5
	v_sub_u32_e32 v5, 0, v4
	v_rcp_iflag_f32_e32 v6, v6
	v_add_u32_e32 v7, s14, v3
	v_mul_f32_e32 v6, 0x4f7ffffe, v6
	v_cvt_u32_f32_e32 v6, v6
	v_mul_lo_u32 v3, v5, v6
	v_mul_hi_u32 v3, v6, v3
	v_add_u32_e32 v3, v6, v3
	v_mul_hi_u32 v3, v7, v3
	v_mul_lo_u32 v5, v3, v4
	v_sub_u32_e32 v5, v7, v5
	v_add_u32_e32 v6, 1, v3
	v_cmp_ge_u32_e32 vcc, v5, v4
	s_nop 1
	v_cndmask_b32_e32 v3, v3, v6, vcc
	v_sub_u32_e32 v6, v5, v4
	v_cndmask_b32_e32 v5, v5, v6, vcc
	v_add_u32_e32 v6, 1, v3
	v_cmp_ge_u32_e32 vcc, v5, v4
	v_add_u32_e32 v5, 1, v7
	s_nop 0
	v_cndmask_b32_e32 v3, v3, v6, vcc
	v_mul_lo_u32 v6, v4, v3
	v_add_u32_e32 v4, v6, v4
	v_cmp_ne_u32_e32 vcc, v5, v4
	s_and_saveexec_b64 s[14:15], vcc
	s_xor_b64 s[14:15], exec, s[14:15]
	s_cbranch_execz .LBB0_1747
	s_waitcnt lgkmcnt(0)
	s_add_u32 s20, s30, 0x7500
	s_addc_u32 s21, s31, 0
	v_mov_b32_e32 v2, 0
	global_load_dword v2, v2, s[20:21] sc1
	s_waitcnt vmcnt(0)
	v_cmp_eq_u32_e32 vcc, v2, v3
	s_and_saveexec_b64 s[16:17], vcc
	s_cbranch_execz .LBB0_1746
	s_add_u32 s18, s30, 0x4200
	s_addc_u32 s19, s31, 0
	s_mov_b32 s27, 1
	s_mov_b64 s[24:25], 0
	v_mov_b32_e32 v2, 0
	s_branch .LBB0_1737

.LBB0_2027:
	s_or_b64 exec, exec, s[18:19]
	v_cvt_f32_u32_e32 v6, v4
	s_waitcnt vmcnt(0)
	v_readfirstlane_b32 s16, v5
	v_sub_u32_e32 v5, 0, v4
	v_rcp_iflag_f32_e32 v6, v6
	v_add_u32_e32 v7, s16, v3
	v_mul_f32_e32 v6, 0x4f7ffffe, v6
	v_cvt_u32_f32_e32 v6, v6
	v_mul_lo_u32 v3, v5, v6
	v_mul_hi_u32 v3, v6, v3
	v_add_u32_e32 v3, v6, v3
	v_mul_hi_u32 v3, v7, v3
	v_mul_lo_u32 v5, v3, v4
	v_sub_u32_e32 v5, v7, v5
	v_add_u32_e32 v6, 1, v3
	v_cmp_ge_u32_e32 vcc, v5, v4
	s_nop 1
	v_cndmask_b32_e32 v3, v3, v6, vcc
	v_sub_u32_e32 v6, v5, v4
	v_cndmask_b32_e32 v5, v5, v6, vcc
	v_add_u32_e32 v6, 1, v3
	v_cmp_ge_u32_e32 vcc, v5, v4
	v_add_u32_e32 v5, 1, v7
	s_nop 0
	v_cndmask_b32_e32 v3, v3, v6, vcc
	v_mul_lo_u32 v6, v4, v3
	v_add_u32_e32 v4, v6, v4
	v_cmp_ne_u32_e32 vcc, v5, v4
	s_and_saveexec_b64 s[16:17], vcc
	s_xor_b64 s[16:17], exec, s[16:17]
	s_cbranch_execz .LBB0_2041
	s_waitcnt lgkmcnt(0)
	s_add_u32 s24, s30, 0x7500
	s_addc_u32 s25, s31, 0
	v_mov_b32_e32 v2, 0
	global_load_dword v2, v2, s[24:25] sc1
	s_waitcnt vmcnt(0)
	v_cmp_eq_u32_e32 vcc, v2, v3
	s_and_saveexec_b64 s[18:19], vcc
	s_cbranch_execz .LBB0_2040
	s_add_u32 s20, s30, 0x4200
	s_addc_u32 s21, s31, 0
	s_mov_b32 s27, 1
	s_mov_b64 s[44:45], 0
	v_mov_b32_e32 v2, 0
	s_branch .LBB0_2031
